# stick-breaking unit loop: workgroup barrier moved after the next unit's first 10 global loads are issued, header vmcnt(2) peeled to the pre-header (no store-ack wait between units)
# baseline (speedup 1.0000x reference)
; __device__ __forceinline__ void sb_unit(int b, int h, int q0, const bf16_t* Q, const bf16_t* __restrict__ K, const bf16_t* __restrict__ V, bf16_t* O, LAS unsigned char* lds, int tid) {
;     const int lane = tid & 63, wave = __builtin_amdgcn_readfirstlane(tid >> 6);
;     const int kt_hi = (q0 >> 5) + 8, kt_lo = kt_hi - SB_WIN > 0 ? kt_hi - SB_WIN : 0, nch = (kt_hi - kt_lo) * 256;
;     const bf16_t* Kh = K + ((size_t)b * SEQ + kt_lo * 32) * DM + h * 64; const bf16_t* Vh = V + ((size_t)b * SEQ + kt_lo * 32) * DM + h * 64;
;     bf16x8_t qr[4];
; #pragma unroll
;     for (int d0 = 0; d0 < 4; ++d0) qr[d0] = *(const bf16x8_t*)(Q + ((size_t)b * SEQ + q0 + wave * 32 + (lane & 31)) * DM + h * 64 + d0 * 16 + (lane >> 5) * 8);
; #pragma unroll
;     for (int hb = 0; hb < 2; ++hb) {
;         u32x4 kq[4], vq[4];
; #pragma unroll
;         for (int i = 0; i < 4; ++i) { const int idx = tid + MEGA_THREADS * (4 * hb + i), row = idx >> 3, c16 = idx & 7;
;             const int rc = idx < nch ? row : 0; kq[i] = *(const u32x4*)(Kh + (size_t)rc * DM + c16 * 8); vq[i] = *(const u32x4*)(Vh + (size_t)rc * DM + c16 * 8); }
; __global__ void __launch_bounds__(MEGA_THREADS, 2) mega(MArgs a) {
;     ...
;                 if (EN_SB && (sub & SUB_SB))
; #pragma unroll 1
;                 for (int k = 0; k < 4; ++k) { const int bh = vcu >> 3, qb = (vcu & 7) * 4 + k; sb_unit(bh >> 4, bh & 15, qb * 256, SQ, SK, SV, H, lds, tid); }
.LBB9_552:
	s_bitcmp0_b32 s71, 5
	s_cbranch_scc1 .LBB9_581
	v_readlane_b32 s12, v254, 37
	s_ashr_i32 s4, s12, 7
	v_readlane_b32 s3, v254, 49
	s_lshl_b32 s2, s12, 2
	s_ashr_i32 s5, s4, 31
	s_and_b32 s3, s3, 0x3c0
	s_and_b32 s2, s2, 28
	s_lshl_b64 s[72:73], s[4:5], 13
	s_lshl_b32 s3, s3, 1
	s_add_u32 s6, s76, s3
	v_lshrrev_b32_e32 v0, 1, v228
	s_addc_u32 s7, s77, 0
	v_and_b32_e32 v0, 16, v0
	v_lshl_add_u64 v[2:3], s[6:7], 0, v[0:1]
	s_mov_b64 s[6:7], 0xc100000
	v_lshl_add_u64 v[78:79], v[2:3], 0, s[6:7]
	v_readlane_b32 s6, v254, 53
	v_readlane_b32 s7, v254, 54
	s_add_u32 s6, s6, s3
	s_addc_u32 s7, s7, 0
	v_readlane_b32 s8, v254, 55
	s_add_u32 s8, s8, s3
	v_readlane_b32 s9, v254, 56
	s_addc_u32 s9, s9, 0
	v_and_b32_e32 v0, 0x70, v34
	s_lshl_b64 s[4:5], s[4:5], 24
	v_lshl_add_u64 v[80:81], s[6:7], 0, v[0:1]
	v_lshl_add_u64 v[82:83], s[8:9], 0, v[0:1]
	v_and_b32_e32 v0, 7, v228
	s_add_u32 s10, s94, s4
	s_waitcnt vmcnt(16)
	v_lshl_add_u32 v8, v0, 4, 0
	v_lshlrev_b32_e32 v0, 9, v228
	s_addc_u32 s11, s95, s5
	v_and_b32_e32 v94, 31, v228
	v_and_b32_e32 v0, 0x800, v0
	s_add_u32 s10, s10, s3
	s_waitcnt vmcnt(15)
	v_add_u32_e32 v9, 0, v0
	s_waitcnt vmcnt(13)
	v_lshrrev_b32_e32 v11, 5, v248
	s_addc_u32 s11, s11, 0
	v_lshlrev_b32_e32 v0, 1, v94
	v_lshl_add_u64 v[2:3], s[10:11], 0, v[0:1]
	v_lshlrev_b32_e32 v0, 13, v11
	v_lshl_add_u64 v[84:85], v[2:3], 0, v[0:1]
	v_ashrrev_i32_e32 v2, 3, v228
	v_ashrrev_i32_e32 v3, 31, v2
	s_movk_i32 s3, 0x90
	v_add_u32_e32 v95, 0x200, v228
	v_lshlrev_b64 v[4:5], 10, v[2:3]
	s_waitcnt vmcnt(12)
	v_mul_lo_u32 v12, v2, s3
	v_lshlrev_b32_e32 v2, 6, v2
	v_ashrrev_i32_e32 v96, 3, v95
	v_and_b32_e32 v0, 0xfffff000, v34
	v_and_b32_e32 v2, 0x7c0, v2
	v_add_u32_e32 v97, 0x400, v228
	v_add3_u32 v13, v9, v0, v2
	v_lshlrev_b32_e32 v0, 4, v95
	v_lshlrev_b32_e32 v2, 6, v96
	v_ashrrev_i32_e32 v98, 3, v97
	v_and_b32_e32 v0, 0xfffff000, v0
	v_and_b32_e32 v2, 0x7c0, v2
	v_add_u32_e32 v99, 0x600, v228
	s_waitcnt vmcnt(11)
	v_add3_u32 v15, v9, v0, v2
	v_lshlrev_b32_e32 v0, 4, v97
	v_lshlrev_b32_e32 v2, 6, v98
	v_ashrrev_i32_e32 v100, 3, v99
	v_and_b32_e32 v0, 0xfffff000, v0
	v_and_b32_e32 v2, 0x7c0, v2
	s_waitcnt vmcnt(8)
	v_add3_u32 v17, v9, v0, v2
	v_lshlrev_b32_e32 v0, 4, v99
	v_lshlrev_b32_e32 v2, 6, v100
	v_add_u32_e32 v101, 0x800, v228
	v_and_b32_e32 v0, 0xfffff000, v0
	v_and_b32_e32 v2, 0x7c0, v2
	s_waitcnt vmcnt(7)
	v_add3_u32 v19, v9, v0, v2
	v_ashrrev_i32_e32 v2, 3, v101
	v_ashrrev_i32_e32 v3, 31, v2
	v_add_u32_e32 v102, 0xa00, v228
	v_lshlrev_b64 v[6:7], 10, v[2:3]
	s_waitcnt vmcnt(6)
	v_mul_lo_u32 v20, v2, s3
	v_lshlrev_b32_e32 v0, 4, v101
	v_lshlrev_b32_e32 v2, 6, v2
	v_ashrrev_i32_e32 v103, 3, v102
	v_and_b32_e32 v0, 0xfffff000, v0
	v_and_b32_e32 v2, 0x7c0, v2
	v_add_u32_e32 v104, 0xc00, v228
	s_waitcnt vmcnt(5)
	v_add3_u32 v21, v9, v0, v2
	v_lshlrev_b32_e32 v0, 4, v102
	v_lshlrev_b32_e32 v2, 6, v103
	v_ashrrev_i32_e32 v105, 3, v104
	v_and_b32_e32 v0, 0xfffff000, v0
	v_and_b32_e32 v2, 0x7c0, v2
	v_add_u32_e32 v106, 0xe00, v228
	v_add3_u32 v23, v9, v0, v2
	v_lshlrev_b32_e32 v0, 4, v104
	v_lshlrev_b32_e32 v2, 6, v105
	v_ashrrev_i32_e32 v107, 3, v106
	v_and_b32_e32 v0, 0xfffff000, v0
	v_and_b32_e32 v2, 0x7c0, v2
	v_add3_u32 v25, v9, v0, v2
	v_lshlrev_b32_e32 v0, 4, v106
	v_lshlrev_b32_e32 v2, 6, v107
	v_and_b32_e32 v0, 0xfffff000, v0
	v_and_b32_e32 v2, 0x7c0, v2
	s_add_u32 s8, s8, s4
	v_lshlrev_b32_e32 v28, 4, v248
	v_add3_u32 v9, v9, v0, v2
	s_addc_u32 s9, s9, s5
	v_and_b32_e32 v2, 0x70, v28
	v_mov_b32_e32 v3, v1
	s_add_u32 s4, s6, s4
	v_lshl_add_u64 v[88:89], s[8:9], 0, v[2:3]
	v_lshlrev_b32_e32 v2, 9, v248
	s_addc_u32 s5, s7, s5
	v_lshlrev_b32_e32 v0, 4, v11
	v_and_b32_e32 v108, 0x800, v2
	v_lshlrev_b32_e32 v2, 1, v248
	v_lshrrev_b32_e32 v115, 3, v248
	v_and_b32_e32 v10, 48, v34
	v_mul_lo_u32 v14, v96, s3
	v_mul_lo_u32 v16, v98, s3
	v_mul_lo_u32 v18, v100, s3
	s_waitcnt vmcnt(4)
	v_mul_lo_u32 v22, v103, s3
	v_mul_lo_u32 v24, v105, s3
	v_mul_lo_u32 v26, v107, s3
	v_lshl_add_u64 v[86:87], s[4:5], 0, v[0:1]
	v_lshlrev_b32_e32 v27, 3, v248
	v_and_b32_e32 v113, 32, v2
	v_lshlrev_b32_e32 v116, 6, v115
	s_and_b32 s3, s12, 7
	v_mul_u32_u24_e32 v2, 0x90, v94
	v_readlane_b32 s4, v254, 23
	v_and_b32_e32 v109, 48, v28
	v_lshlrev_b32_e32 v110, 2, v11
	v_cmp_gt_u32_e64 s[6:7], 32, v248
	v_lshlrev_b32_e32 v111, 8, v11
	v_and_b32_e32 v112, 0xc0, v28
	v_and_b32_e32 v114, 24, v27
	v_or_b32_e32 v117, 0x200, v116
	v_or_b32_e32 v118, 0x400, v116
	v_or_b32_e32 v119, 0x600, v116
	s_lshl_b32 s3, s3, 5
	v_add3_u32 v120, v2, v0, s4
	s_mov_b32 s4, 0
	v_lshlrev_b64 v[90:91], 1, v[4:5]
	v_add_u32_e32 v121, v8, v12
	v_add_u32_e32 v122, v13, v10
	v_add_u32_e32 v123, v8, v14
	v_add_u32_e32 v124, v15, v10
	v_add_u32_e32 v125, v8, v16
	v_add_u32_e32 v126, v17, v10
	v_add_u32_e32 v127, v8, v18
	v_add_u32_e32 v128, v19, v10
	v_lshlrev_b64 v[92:93], 1, v[6:7]
	v_add_u32_e32 v129, v8, v20
	v_add_u32_e32 v130, v21, v10
	v_add_u32_e32 v131, v8, v22
	v_add_u32_e32 v132, v23, v10
	v_add_u32_e32 v133, v8, v24
	v_add_u32_e32 v134, v25, v10
	v_add_u32_e32 v135, v8, v26
	v_add_u32_e32 v136, v9, v10
	s_waitcnt vmcnt(2)
	s_branch .LBB9_556

; __device__ __forceinline__ bf16_t f2bf(float f) { unsigned u = __float_as_uint(f); return (bf16_t)((u + 0x7fffu + ((u >> 16) & 1u)) >> 16); }
; #define LAS __attribute__((address_space(3)))
; __device__ __forceinline__ void sb_wave(int b, int h, int qw0, int kt_lo, const bf16x8_t (&qr)[4], const bf16_t* __restrict__ K, const bf16_t* __restrict__ V, bf16_t* O, LAS unsigned char* lds, int wave, int lane) {
;     ...
;     bf16_t* Ow = O + (rowbase + qw0) * DM + h * 64;
; #pragma unroll
;     for (int r = 0; r < 16; ++r) { const int q = (r & 3) + 8 * (r >> 2) + 4 * hi; Ow[(size_t)q * DM + r32] = f2bf(o0[r]); Ow[(size_t)q * DM + 32 + r32] = f2bf(o1[r]); }
; __device__ __forceinline__ void sb_unit(int b, int h, int q0, const bf16_t* Q, const bf16_t* __restrict__ K, const bf16_t* __restrict__ V, bf16_t* O, LAS unsigned char* lds, int tid) {
;     const int lane = tid & 63, wave = __builtin_amdgcn_readfirstlane(tid >> 6);
;     const int kt_hi = (q0 >> 5) + 8, kt_lo = kt_hi - SB_WIN > 0 ? kt_hi - SB_WIN : 0, nch = (kt_hi - kt_lo) * 256;
;     const bf16_t* Kh = K + ((size_t)b * SEQ + kt_lo * 32) * DM + h * 64; const bf16_t* Vh = V + ((size_t)b * SEQ + kt_lo * 32) * DM + h * 64;
;     bf16x8_t qr[4];
; #pragma unroll
;     for (int d0 = 0; d0 < 4; ++d0) qr[d0] = *(const bf16x8_t*)(Q + ((size_t)b * SEQ + q0 + wave * 32 + (lane & 31)) * DM + h * 64 + d0 * 16 + (lane >> 5) * 8);
; #pragma unroll
;     for (int hb = 0; hb < 2; ++hb) {
;         u32x4 kq[4], vq[4];
; #pragma unroll
;         for (int i = 0; i < 4; ++i) { const int idx = tid + MEGA_THREADS * (4 * hb + i), row = idx >> 3, c16 = idx & 7;
;             const int rc = idx < nch ? row : 0; kq[i] = *(const u32x4*)(Kh + (size_t)rc * DM + c16 * 8); vq[i] = *(const u32x4*)(Vh + (size_t)rc * DM + c16 * 8); }
; #pragma unroll
;         for (int i = 0; i < 4; ++i) { const int idx = tid + MEGA_THREADS * (4 * hb + i), row = idx >> 3, c16 = idx & 7;
;             if (idx < nch) { *(LAS u32x4*)(lds + SB_KOFF + row * 144 + c16 * 16) = kq[i];
;                 *(LAS u32x4*)(lds + SB_VOFF + (row >> 5) * 4096 + (c16 >> 2) * 2048 + (row & 31) * 64 + (c16 & 3) * 16) = vq[i]; } }
.LBB9_555:
	s_ashr_i32 s67, s66, 31
	s_lshl_b64 s[8:9], s[66:67], 11
	s_nop 3
	v_readfirstlane_b32 s5, v228
	s_ashr_i32 s5, s5, 6
	s_lshl_b32 s5, s5, 12
	s_add_i32 s5, s5, 0x1ba00
	v_and_b32_e32 v0, 31, v244
	v_lshrrev_b32_e32 v34, 5, v244
	v_lshlrev_b32_e32 v0, 1, v0
	v_lshl_add_u32 v34, v34, 9, v0
	v_add_u32_e32 v34, s5, v34
	v_lshl_add_u32 v35, v244, 4, s5
	v_cvt_pk_bf16_f32 v2, v2, v2
	ds_write_b16 v34, v2 offset:0
	v_cvt_pk_bf16_f32 v18, v18, v18
	ds_write_b16 v34, v18 offset:64
	v_cvt_pk_bf16_f32 v3, v3, v3
	ds_write_b16 v34, v3 offset:128
	v_cvt_pk_bf16_f32 v19, v19, v19
	ds_write_b16 v34, v19 offset:192
	v_cvt_pk_bf16_f32 v4, v4, v4
	ds_write_b16 v34, v4 offset:256
	v_cvt_pk_bf16_f32 v20, v20, v20
	ds_write_b16 v34, v20 offset:320
	v_cvt_pk_bf16_f32 v5, v5, v5
	ds_write_b16 v34, v5 offset:384
	v_cvt_pk_bf16_f32 v21, v21, v21
	ds_write_b16 v34, v21 offset:448
	v_cvt_pk_bf16_f32 v6, v6, v6
	ds_write_b16 v34, v6 offset:1024
	v_cvt_pk_bf16_f32 v22, v22, v22
	ds_write_b16 v34, v22 offset:1088
	v_cvt_pk_bf16_f32 v7, v7, v7
	ds_write_b16 v34, v7 offset:1152
	v_cvt_pk_bf16_f32 v23, v23, v23
	ds_write_b16 v34, v23 offset:1216
	v_cvt_pk_bf16_f32 v8, v8, v8
	ds_write_b16 v34, v8 offset:1280
	v_cvt_pk_bf16_f32 v24, v24, v24
	ds_write_b16 v34, v24 offset:1344
	v_cvt_pk_bf16_f32 v9, v9, v9
	ds_write_b16 v34, v9 offset:1408
	v_cvt_pk_bf16_f32 v25, v25, v25
	ds_write_b16 v34, v25 offset:1472
	v_cvt_pk_bf16_f32 v10, v10, v10
	ds_write_b16 v34, v10 offset:2048
	v_cvt_pk_bf16_f32 v26, v26, v26
	ds_write_b16 v34, v26 offset:2112
	v_cvt_pk_bf16_f32 v11, v11, v11
	ds_write_b16 v34, v11 offset:2176
	v_cvt_pk_bf16_f32 v27, v27, v27
	ds_write_b16 v34, v27 offset:2240
	v_cvt_pk_bf16_f32 v12, v12, v12
	ds_write_b16 v34, v12 offset:2304
	v_cvt_pk_bf16_f32 v28, v28, v28
	ds_write_b16 v34, v28 offset:2368
	v_cvt_pk_bf16_f32 v13, v13, v13
	ds_write_b16 v34, v13 offset:2432
	v_cvt_pk_bf16_f32 v29, v29, v29
	ds_write_b16 v34, v29 offset:2496
	v_cvt_pk_bf16_f32 v14, v14, v14
	ds_write_b16 v34, v14 offset:3072
	v_cvt_pk_bf16_f32 v30, v30, v30
	ds_write_b16 v34, v30 offset:3136
	v_cvt_pk_bf16_f32 v15, v15, v15
	ds_write_b16 v34, v15 offset:3200
	v_cvt_pk_bf16_f32 v31, v31, v31
	ds_write_b16 v34, v31 offset:3264
	v_cvt_pk_bf16_f32 v16, v16, v16
	ds_write_b16 v34, v16 offset:3328
	v_cvt_pk_bf16_f32 v32, v32, v32
	ds_write_b16 v34, v32 offset:3392
	v_cvt_pk_bf16_f32 v17, v17, v17
	ds_write_b16 v34, v17 offset:3456
	v_cvt_pk_bf16_f32 v33, v33, v33
	ds_write_b16 v34, v33 offset:3520
	s_waitcnt lgkmcnt(0)
	ds_read_b128 v[2:5], v35
	ds_read_b128 v[6:9], v35 offset:1024
	ds_read_b128 v[10:13], v35 offset:2048
	ds_read_b128 v[14:17], v35 offset:3072
	v_and_b32_e32 v0, 31, v244
	v_lshrrev_b32_e32 v18, 5, v244
	v_lshlrev_b32_e32 v0, 1, v0
	v_lshl_add_u32 v0, v18, 13, v0
	v_lshrrev_b32_e32 v18, 3, v244
	v_and_b32_e32 v19, 7, v244
	v_lshlrev_b32_e32 v19, 4, v19
	v_lshl_add_u32 v18, v18, 11, v19
	v_sub_u32_e32 v0, v18, v0
	v_lshl_add_u64 v[34:35], v[84:85], 0, s[8:9]
	v_lshl_add_u64 v[34:35], v[34:35], 0, v[0:1]
	s_mov_b64 s[8:9], 0x4000
	v_lshl_add_u64 v[18:19], v[34:35], 0, s[8:9]
	v_lshl_add_u64 v[20:21], v[18:19], 0, s[8:9]
	v_lshl_add_u64 v[22:23], v[20:21], 0, s[8:9]
	s_waitcnt lgkmcnt(0)
	global_store_dwordx4 v[34:35], v[2:5], off
	global_store_dwordx4 v[18:19], v[6:9], off
	global_store_dwordx4 v[20:21], v[10:13], off
	global_store_dwordx4 v[22:23], v[14:17], off
	s_add_i32 s4, s4, 1
	s_add_i32 s3, s3, 8
	s_cmp_lg_u32 s4, 4
	s_cbranch_scc0 .Lsb_exit_bar
.LBB9_556:
	s_or_b32 s8, s4, s2
	s_lshl_b32 s18, s8, 8
	s_lshl_b32 s8, s8, 3
	v_readfirstlane_b32 s5, v228
	v_sub_u32_e64 v137, s8, 5 clamp
	s_ashr_i32 s5, s5, 6
	s_max_u32 s9, s8, 5
	v_lshlrev_b32_e32 v0, 5, v137
	s_sub_i32 s8, s8, s9
	v_lshl_add_u64 v[2:3], s[72:73], 0, v[0:1]
	s_lshl_b32 s14, s5, 5
	v_or_b32_e32 v0, s18, v94
	s_lshl_b32 s8, s8, 8
	s_ashr_i32 s15, s14, 31
	v_or_b32_e32 v4, s72, v0
	v_mov_b32_e32 v5, s73
	v_lshl_add_u64 v[4:5], v[4:5], 0, s[14:15]
	s_add_i32 s15, s8, 0xd00
	v_lshlrev_b64 v[2:3], 11, v[2:3]
	v_cmp_gt_i32_e32 vcc, s15, v95
	v_cmp_gt_i32_e64 s[8:9], s15, v97
	v_cmp_gt_i32_e64 s[10:11], s15, v99
	v_lshlrev_b64 v[4:5], 11, v[4:5]
	v_lshl_add_u64 v[26:27], v[80:81], 0, v[2:3]
	v_lshl_add_u64 v[28:29], v[82:83], 0, v[2:3]
	v_cndmask_b32_e32 v2, 0, v96, vcc
	v_cndmask_b32_e64 v10, 0, v98, s[8:9]
	v_cndmask_b32_e64 v18, 0, v100, s[10:11]
	v_lshl_add_u64 v[4:5], v[78:79], 0, v[4:5]
	v_ashrrev_i32_e32 v3, 31, v2
	v_ashrrev_i32_e32 v11, 31, v10
	v_ashrrev_i32_e32 v19, 31, v18
	global_load_dwordx4 v[50:53], v[4:5], off
	global_load_dwordx4 v[54:57], v[4:5], off offset:32
	global_load_dwordx4 v[58:61], v[4:5], off offset:64
	global_load_dwordx4 v[62:65], v[4:5], off offset:96
	v_lshlrev_b64 v[2:3], 11, v[2:3]
	v_lshlrev_b64 v[10:11], 11, v[10:11]
	v_lshlrev_b64 v[18:19], 11, v[18:19]
	v_lshl_add_u64 v[4:5], v[26:27], 0, v[2:3]
	v_lshl_add_u64 v[6:7], v[28:29], 0, v[2:3]
	v_lshl_add_u64 v[12:13], v[26:27], 0, v[10:11]
	v_lshl_add_u64 v[14:15], v[28:29], 0, v[10:11]
	v_lshl_add_u64 v[20:21], v[26:27], 0, v[18:19]
	v_lshl_add_u64 v[22:23], v[28:29], 0, v[18:19]
	global_load_dwordx4 v[2:5], v[4:5], off
	s_nop 0
	global_load_dwordx4 v[6:9], v[6:7], off
	s_nop 0
	global_load_dwordx4 v[10:13], v[12:13], off
	s_nop 0
	global_load_dwordx4 v[14:17], v[14:15], off
	s_nop 0
	global_load_dwordx4 v[18:21], v[20:21], off
	s_nop 0
	global_load_dwordx4 v[22:25], v[22:23], off
	s_barrier
	v_cmp_gt_i32_e64 s[12:13], s15, v228
	s_and_saveexec_b64 s[16:17], s[12:13]
	s_cbranch_execz .LBB9_560
	v_lshl_add_u64 v[34:35], v[28:29], 0, v[90:91]
	v_lshl_add_u64 v[30:31], v[26:27], 0, v[90:91]
	global_load_dwordx4 v[30:33], v[30:31], off
	s_nop 0
	global_load_dwordx4 v[34:37], v[34:35], off
	s_waitcnt vmcnt(1)
	ds_write_b128 v121, v[30:33]
	s_waitcnt vmcnt(0)
	ds_write_b128 v122, v[34:37] offset:59904
	s_or_b64 exec, exec, s[16:17]
	s_and_saveexec_b64 s[12:13], vcc
	s_cbranch_execnz .LBB9_561

; __device__ __forceinline__ void sb_wave(int b, int h, int qw0, int kt_lo, const bf16x8_t (&qr)[4], const bf16_t* __restrict__ K, const bf16_t* __restrict__ V, bf16_t* O, LAS unsigned char* lds, int wave, int lane) {
;     ...
;     f32x16_t o0 = {}, o1 = {}; float R = 0.f; const int qabs = qw0 + r32;
; __device__ __forceinline__ void sb_unit(int b, int h, int q0, const bf16_t* Q, const bf16_t* __restrict__ K, const bf16_t* __restrict__ V, bf16_t* O, LAS unsigned char* lds, int tid) {
;     ...
;     __syncthreads();
; }
.LBB9_579:
	s_waitcnt vmcnt(2)
	v_mov_b32_e32 v17, 0
	v_mov_b32_e32 v16, v17
	v_mov_b32_e32 v15, v17
	v_mov_b32_e32 v14, v17
	v_mov_b32_e32 v13, v17
	v_mov_b32_e32 v12, v17
	v_mov_b32_e32 v11, v17
	v_mov_b32_e32 v10, v17
	v_mov_b32_e32 v9, v17
	v_mov_b32_e32 v8, v17
	v_mov_b32_e32 v7, v17
	v_mov_b32_e32 v6, v17
	v_mov_b32_e32 v5, v17
	v_mov_b32_e32 v4, v17
	v_mov_b32_e32 v3, v17
	v_mov_b32_e32 v2, v17
	v_mov_b32_e32 v33, v17
	v_mov_b32_e32 v32, v17
	v_mov_b32_e32 v31, v17
	v_mov_b32_e32 v30, v17
	v_mov_b32_e32 v29, v17
	v_mov_b32_e32 v28, v17
	v_mov_b32_e32 v27, v17
	v_mov_b32_e32 v26, v17
	s_waitcnt vmcnt(0)
	v_mov_b32_e32 v25, v17
	v_mov_b32_e32 v24, v17
	v_mov_b32_e32 v23, v17
	v_mov_b32_e32 v22, v17
	v_mov_b32_e32 v21, v17
	v_mov_b32_e32 v20, v17
	v_mov_b32_e32 v19, v17
	v_mov_b32_e32 v18, v17
	s_branch .LBB9_555
.Lsb_exit_bar:
	s_barrier
.LBB9_580:
	v_readlane_b32 s72, v254, 28
	s_movk_i32 s73, 0x2c00
